# MLA attention unit epilogue: masked-tile MFMA skip extended to QK(NT-1), PV(NT-2), PV(NT-1)
# baseline (speedup 1.0000x reference)
; template <bool BAND> DI void partialSM(f32x16& p0, f32x16& p1, float& m_reg, float& mn, float& alpha, bool masked, const LAS float* tb, float C) {
;     ...
;   float pmax = p0[0];
; #pragma unroll
;   for (int r = 1; r < 16; ++r) pmax = fmaxf(pmax, p0[r]);
; #pragma unroll
;   for (int r = 0; r < 16; ++r) pmax = fmaxf(pmax, p1[r]);
;   { auto rr = __builtin_amdgcn_permlane32_swap(__float_as_uint(pmax), __float_as_uint(pmax), false, false);
;     pmax = fmaxf(__uint_as_float(rr[0]), __uint_as_float(rr[1])); }
;   if (__builtin_expect(__all(pmax - m_reg <= THRP), 1)) { mn = m_reg; alpha = 1.f; }
;   else { mn = fmaxf(m_reg, pmax); alpha = __builtin_amdgcn_exp2f((m_reg - mn) * CC); m_reg = mn; }
; DI void finishSM(f32x16& p0, f32x16& p1, float alpha, float& l_reg, bf16x8& pa0, bf16x8& pa1, bf16x8& pa2, bf16x8& pa3) {
; #pragma unroll
;   for (int r = 0; r < 16; ++r) p1[r] = __builtin_amdgcn_exp2f(p1[r]);
;   float ps = 0;
; #pragma unroll
;   for (int r = 0; r < 16; ++r) ps += p0[r];
; #pragma unroll
;   for (int r = 0; r < 16; ++r) ps += p1[r];
;   { auto rr = __builtin_amdgcn_permlane32_swap(__float_as_uint(ps), __float_as_uint(ps), false, false);
;     ps = __uint_as_float(rr[0]) + __uint_as_float(rr[1]); }
;   l_reg = l_reg * alpha + ps;
;     ...
;   PK4(p0, 0, pa0); PK4(p0, 8, pa1); PK4(p1, 0, pa2); PK4(p1, 8, pa3);
.Lqsme_skip:
	s_waitcnt lgkmcnt(0)
	v_add_f32_e32 v112, 0, v110
	v_exp_f32_e32 v114, v175
	v_exp_f32_e32 v115, v172
	v_cvt_pk_bf16_f32 v132, v110, v111
	v_add_f32_e32 v110, v111, v112
	v_add_f32_e32 v110, v108, v110
	v_cvt_pk_bf16_f32 v133, v108, v109
	v_add_f32_e32 v108, v109, v110
	v_add_f32_e32 v108, v106, v108
	v_cvt_pk_bf16_f32 v134, v106, v107
	v_add_f32_e32 v106, v107, v108
	v_add_f32_e32 v106, v72, v106
	v_add_f32_e32 v106, v73, v106
	v_add_f32_e32 v106, v66, v106
	v_add_f32_e32 v106, v67, v106
	v_add_f32_e32 v106, v64, v106
	v_add_f32_e32 v106, v65, v106
	v_exp_f32_e32 v108, v196
	v_add_f32_e32 v106, v68, v106
	v_exp_f32_e32 v109, v197
	v_add_f32_e32 v106, v69, v106
	v_exp_f32_e32 v110, v178
	v_add_f32_e32 v106, v70, v106
	v_exp_f32_e32 v111, v179
	v_add_f32_e32 v106, v71, v106
	v_exp_f32_e32 v112, v174
	v_add_f32_e32 v106, v108, v106
	v_add_f32_e32 v106, v109, v106
	v_add_f32_e32 v106, v110, v106
	v_exp_f32_e32 v128, v173
	v_add_f32_e32 v106, v111, v106
	v_exp_f32_e32 v129, v170
	v_add_f32_e32 v106, v112, v106
	v_exp_f32_e32 v130, v171
	v_add_f32_e32 v106, v114, v106
	v_exp_f32_e32 v131, v168
	v_add_f32_e32 v106, v115, v106
	v_exp_f32_e32 v136, v169
	v_add_f32_e32 v106, v128, v106
	v_exp_f32_e32 v137, v166
	v_add_f32_e32 v106, v129, v106
	v_exp_f32_e32 v138, v167
	v_add_f32_e32 v106, v130, v106
	v_exp_f32_e32 v139, v164
	v_add_f32_e32 v106, v131, v106
	v_exp_f32_e32 v140, v165
	v_add_f32_e32 v106, v136, v106
	v_add_f32_e32 v106, v137, v106
	v_add_f32_e32 v106, v138, v106
	v_add_f32_e32 v106, v139, v106
	v_add_f32_e32 v106, v140, v106
	v_mov_b32_e32 v107, v106
	v_cvt_pk_bf16_f32 v135, v72, v73
	v_cvt_pk_bf16_f32 v66, v66, v67
	v_cvt_pk_bf16_f32 v67, v64, v65
	v_cvt_pk_bf16_f32 v68, v68, v69
	v_cvt_pk_bf16_f32 v69, v70, v71
	v_permlane32_swap_b32_e32 v106, v107
	v_permlane32_swap_b32_e32 v66, v68
	v_permlane32_swap_b32_e32 v67, v69
	v_cvt_pk_bf16_f32 v108, v108, v109
	v_cvt_pk_bf16_f32 v109, v110, v111
	v_cvt_pk_bf16_f32 v110, v112, v114
	v_cvt_pk_bf16_f32 v111, v115, v128
	v_cvt_pk_bf16_f32 v120, v129, v130
	v_cvt_pk_bf16_f32 v121, v131, v136
	v_cvt_pk_bf16_f32 v122, v137, v138
	v_cvt_pk_bf16_f32 v123, v139, v140
	v_permlane32_swap_b32_e32 v132, v134
	v_permlane32_swap_b32_e32 v133, v135
	v_permlane32_swap_b32_e32 v108, v110
	v_permlane32_swap_b32_e32 v109, v111
	v_permlane32_swap_b32_e32 v120, v122
	v_permlane32_swap_b32_e32 v121, v123
	s_branch .Lqsme_join
.Lpvme_skip:
	s_waitcnt lgkmcnt(0)
	s_nop 0
	s_add_i32 s14, s19, -1
	s_cmp_le_i32 s19, s12
	s_cselect_b64 s[12:13], -1, 0
	s_cmp_gt_i32 s14, s21
	s_cselect_b64 s[14:15], -1, 0
	s_or_b64 vcc, s[12:13], s[14:15]
	v_cndmask_b32_e32 v74, v74, v211, vcc
	v_cndmask_b32_e32 v75, v75, v211, vcc
	v_cndmask_b32_e32 v69, v94, v211, vcc
	v_cndmask_b32_e32 v94, v95, v211, vcc
	v_max_f32_e32 v64, v75, v75
	v_max_f32_e32 v95, v74, v74
	v_cndmask_b32_e32 v76, v76, v211, vcc
	v_cndmask_b32_e32 v77, v77, v211, vcc
	v_max_f32_e32 v64, v95, v64
	v_cndmask_b32_e32 v78, v78, v211, vcc
	v_cndmask_b32_e32 v79, v79, v211, vcc
	v_max3_f32 v64, v64, v76, v77
	v_cndmask_b32_e32 v80, v80, v211, vcc
	v_cndmask_b32_e32 v81, v81, v211, vcc
	v_max3_f32 v64, v64, v78, v79
	v_cndmask_b32_e32 v82, v82, v211, vcc
	v_cndmask_b32_e32 v83, v83, v211, vcc
	v_max3_f32 v64, v64, v80, v81
	v_cndmask_b32_e32 v84, v84, v211, vcc
	v_cndmask_b32_e32 v85, v85, v211, vcc
	v_max3_f32 v64, v64, v82, v83
	v_cndmask_b32_e32 v86, v86, v211, vcc
	v_cndmask_b32_e32 v87, v87, v211, vcc
	v_max3_f32 v64, v64, v84, v85
	v_cndmask_b32_e32 v88, v88, v211, vcc
	v_cndmask_b32_e32 v89, v89, v211, vcc
	v_max3_f32 v64, v64, v86, v87
	v_cndmask_b32_e32 v90, v90, v211, vcc
	v_cndmask_b32_e32 v91, v91, v211, vcc
	v_max3_f32 v64, v64, v88, v89
	v_cndmask_b32_e32 v92, v92, v211, vcc
	v_cndmask_b32_e32 v93, v93, v211, vcc
	v_max3_f32 v64, v64, v90, v91
	v_max3_f32 v64, v64, v92, v93
	v_cndmask_b32_e32 v67, v96, v211, vcc
	v_cndmask_b32_e32 v68, v97, v211, vcc
	v_max3_f32 v64, v64, v69, v94
	v_cndmask_b32_e32 v98, v98, v211, vcc
	v_cndmask_b32_e32 v66, v99, v211, vcc
	v_max3_f32 v64, v64, v67, v68
	v_cndmask_b32_e32 v73, v100, v211, vcc
	v_cndmask_b32_e32 v100, v101, v211, vcc
	v_max3_f32 v64, v64, v98, v66
	v_cndmask_b32_e32 v72, v102, v211, vcc
	v_cndmask_b32_e32 v71, v103, v211, vcc
	v_max3_f32 v64, v64, v73, v100
	v_cndmask_b32_e32 v65, v104, v211, vcc
	v_cndmask_b32_e32 v70, v105, v211, vcc
	v_max3_f32 v64, v64, v72, v71
	v_max3_f32 v64, v64, v65, v70
	v_mov_b32_e32 v95, v64
	s_nop 1
	v_permlane32_swap_b32_e32 v64, v95
	v_max_f32_e32 v95, v95, v95
	v_max_f32_e32 v64, v64, v64
	v_max_f32_e32 v95, v64, v95
	v_sub_f32_e32 v64, v95, v203
	v_cmp_ge_f32_e32 vcc, s84, v64
	s_cmp_eq_u64 vcc, exec
	v_mov_b32_e32 v64, 1.0
	s_branch .Lpvme_join
.Lpvmf_skip:
	s_waitcnt lgkmcnt(0)
	s_nop 0
	s_branch .Lpvmf_join
; #define LAS __attribute__((address_space(3)))
; DI void finishSM(f32x16& p0, f32x16& p1, float alpha, float& l_reg, bf16x8& pa0, bf16x8& pa1, bf16x8& pa2, bf16x8& pa3) {
; #pragma unroll
;   for (int r = 0; r < 16; ++r) p1[r] = __builtin_amdgcn_exp2f(p1[r]);
;   float ps = 0;
; #pragma unroll
;   for (int r = 0; r < 16; ++r) ps += p0[r];
; #pragma unroll
;   for (int r = 0; r < 16; ++r) ps += p1[r];
;   { auto rr = __builtin_amdgcn_permlane32_swap(__float_as_uint(ps), __float_as_uint(ps), false, false);
;     ps = __uint_as_float(rr[0]) + __uint_as_float(rr[1]); }
;   l_reg = l_reg * alpha + ps;
;     ...
;   PK4(p0, 0, pa0); PK4(p0, 8, pa1); PK4(p1, 0, pa2); PK4(p1, 8, pa3);
;     ...
; }
; template <int NQ> DI void qkt(f32x16& p0, f32x16& p1, const LAS char* Ks, const LAS char* KRs, const bf16x8* qr, int r32, int hi) {
;   p0 = f32x16{}; p1 = f32x16{};
; #pragma unroll
;   for (int d0 = 0; d0 < 8; ++d0) { const int cb = (d0 * 16 + hi * 8) * 2;
;     const bf16x8 b0 = *(const LAS bf16x8*)(Ks + KSWZ(r32, cb));
;     const bf16x8 b1 = *(const LAS bf16x8*)(Ks + KSWZ(32 + r32, cb));
;     p0 = __builtin_amdgcn_mfma_f32_32x32x16_bf16(b0, qr[d0], p0, 0, 0, 0);
;     p1 = __builtin_amdgcn_mfma_f32_32x32x16_bf16(b1, qr[d0], p1, 0, 0, 0); }
;   if (NQ == 12) {
; #pragma unroll
;     for (int d0 = 0; d0 < 4; ++d0) { const int cb = (d0 * 16 + hi * 8) * 2;
;       const bf16x8 b0 = *(const LAS bf16x8*)(KRs + KRSWZ(r32, cb));
;       const bf16x8 b1 = *(const LAS bf16x8*)(KRs + KRSWZ(32 + r32, cb));
;       p0 = __builtin_amdgcn_mfma_f32_32x32x16_bf16(b0, qr[8 + d0], p0, 0, 0, 0);
;       p1 = __builtin_amdgcn_mfma_f32_32x32x16_bf16(b1, qr[8 + d0], p1, 0, 0, 0); }
;   }
.LBB0_358:
	s_max_i32 s12, s34, 0
	s_cmp_le_i32 s19, s12
	s_cbranch_scc1 .Lqsme_skip
	s_add_i32 s98, s19, -1
	s_cmp_gt_i32 s98, s21
	s_cbranch_scc1 .Lqsme_skip
	ds_read_b128 v[74:77], v207 offset:50176
	ds_read_b128 v[90:93], v207 offset:50208
	v_add_f32_e32 v112, 0, v110
	v_exp_f32_e32 v114, v175
	v_exp_f32_e32 v115, v172
	s_waitcnt lgkmcnt(1)
	v_mfma_f32_32x32x16_bf16 v[74:89], v[74:77], v[160:163], 0
	s_waitcnt lgkmcnt(0)
	v_mfma_f32_32x32x16_bf16 v[74:89], v[90:93], v[156:159], v[74:89]
	ds_read_b128 v[90:93], v207 offset:58880
	s_waitcnt lgkmcnt(0)
	v_mfma_f32_32x32x16_bf16 v[90:105], v[90:93], v[160:163], 0
	ds_read_b128 v[160:163], v207 offset:58912
	s_waitcnt lgkmcnt(0)
	v_mfma_f32_32x32x16_bf16 v[90:105], v[160:163], v[156:159], v[90:105]
	ds_read_b128 v[156:159], v207 offset:50240
	s_waitcnt lgkmcnt(0)
	v_mfma_f32_32x32x16_bf16 v[74:89], v[156:159], v[152:155], v[74:89]
	ds_read_b128 v[156:159], v207 offset:58944
	s_waitcnt lgkmcnt(0)
	v_mfma_f32_32x32x16_bf16 v[90:105], v[156:159], v[152:155], v[90:105]
	ds_read_b128 v[152:155], v207 offset:50272
	s_waitcnt lgkmcnt(0)
	v_mfma_f32_32x32x16_bf16 v[74:89], v[152:155], v[148:151], v[74:89]
	ds_read_b128 v[152:155], v207 offset:58976
	s_waitcnt lgkmcnt(0)
	v_mfma_f32_32x32x16_bf16 v[90:105], v[152:155], v[148:151], v[90:105]
	ds_read_b128 v[148:151], v207 offset:50304
	s_waitcnt lgkmcnt(0)
	v_mfma_f32_32x32x16_bf16 v[74:89], v[148:151], v[144:147], v[74:89]
	ds_read_b128 v[148:151], v207 offset:59008
	s_waitcnt lgkmcnt(0)
	v_mfma_f32_32x32x16_bf16 v[90:105], v[148:151], v[144:147], v[90:105]
	ds_read_b128 v[144:147], v207 offset:50336
	s_waitcnt lgkmcnt(0)
	v_mfma_f32_32x32x16_bf16 v[74:89], v[144:147], v[140:143], v[74:89]
	ds_read_b128 v[144:147], v207 offset:59040
	s_waitcnt lgkmcnt(0)
	v_mfma_f32_32x32x16_bf16 v[90:105], v[144:147], v[140:143], v[90:105]
	ds_read_b128 v[140:143], v207 offset:50368
	s_waitcnt lgkmcnt(0)
	v_mfma_f32_32x32x16_bf16 v[74:89], v[140:143], v[136:139], v[74:89]
	ds_read_b128 v[140:143], v207 offset:59072
	s_waitcnt lgkmcnt(0)
	v_mfma_f32_32x32x16_bf16 v[90:105], v[140:143], v[136:139], v[90:105]
	ds_read_b128 v[136:139], v207 offset:50400
	s_waitcnt lgkmcnt(0)
	v_mfma_f32_32x32x16_bf16 v[74:89], v[136:139], v[132:135], v[74:89]
	ds_read_b128 v[136:139], v207 offset:59104
	s_waitcnt lgkmcnt(0)
	v_mfma_f32_32x32x16_bf16 v[90:105], v[136:139], v[132:135], v[90:105]
	ds_read_b128 v[132:135], v218
	s_waitcnt lgkmcnt(0)
	v_mfma_f32_32x32x16_bf16 v[74:89], v[132:135], v[128:131], v[74:89]
	ds_read_b128 v[134:137], v218 offset:4608
	ds_read_b128 v[138:141], v218 offset:32
	ds_read_b128 v[142:145], v218 offset:4640
	ds_read_b128 v[146:149], v218 offset:64
	ds_read_b128 v[150:153], v218 offset:96
	ds_read_b128 v[154:157], v218 offset:4672
	ds_read_b128 v[158:161], v218 offset:4704
	v_cvt_pk_bf16_f32 v132, v110, v111
	v_add_f32_e32 v110, v111, v112
	v_add_f32_e32 v110, v108, v110
	v_cvt_pk_bf16_f32 v133, v108, v109
	v_add_f32_e32 v108, v109, v110
	v_add_f32_e32 v108, v106, v108
	s_waitcnt lgkmcnt(6)
	v_mfma_f32_32x32x16_bf16 v[90:105], v[134:137], v[128:131], v[90:105]
	v_cvt_pk_bf16_f32 v134, v106, v107
	v_add_f32_e32 v106, v107, v108
	v_add_f32_e32 v106, v72, v106
	v_add_f32_e32 v106, v73, v106
	v_add_f32_e32 v106, v66, v106
	v_add_f32_e32 v106, v67, v106
	v_add_f32_e32 v106, v64, v106
	s_waitcnt lgkmcnt(5)
	v_mfma_f32_32x32x16_bf16 v[74:89], v[138:141], v[124:127], v[74:89]
	v_add_f32_e32 v106, v65, v106
	v_exp_f32_e32 v108, v196
	v_add_f32_e32 v106, v68, v106
	v_exp_f32_e32 v109, v197
	v_add_f32_e32 v106, v69, v106
	v_exp_f32_e32 v110, v178
	v_add_f32_e32 v106, v70, v106
	s_waitcnt lgkmcnt(4)
	v_mfma_f32_32x32x16_bf16 v[90:105], v[142:145], v[124:127], v[90:105]
	v_exp_f32_e32 v111, v179
	v_add_f32_e32 v106, v71, v106
	v_exp_f32_e32 v112, v174
	v_add_f32_e32 v106, v108, v106
	v_add_f32_e32 v106, v109, v106
	v_add_f32_e32 v106, v110, v106
	v_exp_f32_e32 v128, v173
	s_waitcnt lgkmcnt(3)
	v_mfma_f32_32x32x16_bf16 v[74:89], v[146:149], v[120:123], v[74:89]
	v_add_f32_e32 v106, v111, v106
	v_exp_f32_e32 v129, v170
	v_add_f32_e32 v106, v112, v106
	v_exp_f32_e32 v130, v171
	v_add_f32_e32 v106, v114, v106
	v_exp_f32_e32 v131, v168
	v_add_f32_e32 v106, v115, v106
	s_waitcnt lgkmcnt(1)
	v_mfma_f32_32x32x16_bf16 v[90:105], v[154:157], v[120:123], v[90:105]
	v_exp_f32_e32 v136, v169
	v_add_f32_e32 v106, v128, v106
	v_exp_f32_e32 v137, v166
	v_add_f32_e32 v106, v129, v106
	v_exp_f32_e32 v138, v167
	v_add_f32_e32 v106, v130, v106
	v_exp_f32_e32 v139, v164
	v_add_f32_e32 v106, v131, v106
	v_mfma_f32_32x32x16_bf16 v[74:89], v[150:153], v[116:119], v[74:89]
	v_exp_f32_e32 v140, v165
	v_add_f32_e32 v106, v136, v106
	v_add_f32_e32 v106, v137, v106
	v_add_f32_e32 v106, v138, v106
	v_add_f32_e32 v106, v139, v106
	v_add_f32_e32 v106, v140, v106
	v_mov_b32_e32 v107, v106
	s_waitcnt lgkmcnt(0)
	v_mfma_f32_32x32x16_bf16 v[90:105], v[158:161], v[116:119], v[90:105]
	v_cvt_pk_bf16_f32 v135, v72, v73
	v_cvt_pk_bf16_f32 v66, v66, v67
	v_cvt_pk_bf16_f32 v67, v64, v65
	v_cvt_pk_bf16_f32 v68, v68, v69
	v_cvt_pk_bf16_f32 v69, v70, v71
	v_permlane32_swap_b32_e32 v106, v107
	v_permlane32_swap_b32_e32 v66, v68
	v_permlane32_swap_b32_e32 v67, v69
	v_cvt_pk_bf16_f32 v108, v108, v109
	v_cvt_pk_bf16_f32 v109, v110, v111
	v_cvt_pk_bf16_f32 v110, v112, v114
	v_cvt_pk_bf16_f32 v111, v115, v128
	v_cvt_pk_bf16_f32 v120, v129, v130
	v_cvt_pk_bf16_f32 v121, v131, v136
	v_cvt_pk_bf16_f32 v122, v137, v138
	v_cvt_pk_bf16_f32 v123, v139, v140
	v_permlane32_swap_b32_e32 v132, v134
	v_permlane32_swap_b32_e32 v133, v135
	v_permlane32_swap_b32_e32 v108, v110
	v_permlane32_swap_b32_e32 v109, v111
	v_permlane32_swap_b32_e32 v120, v122
	v_permlane32_swap_b32_e32 v121, v123
; #define SBAR() __builtin_amdgcn_sched_barrier(0)
; template <int OFF> DI s16x4 tr_read(int vb) { s16x4 r; asm volatile("ds_read_b64_tr_b16 %0, %1 offset:%2" : "=&v"(r) : "v"(vb), "i"(OFF) : "memory"); return r; }
; template <bool BAND> DI void partialSM(f32x16& p0, f32x16& p1, float& m_reg, float& mn, float& alpha, bool masked, const LAS float* tb, float C) {
;     ...
;   float pmax = p0[0];
; #pragma unroll
;   for (int r = 1; r < 16; ++r) pmax = fmaxf(pmax, p0[r]);
; #pragma unroll
;   for (int r = 0; r < 16; ++r) pmax = fmaxf(pmax, p1[r]);
;   { auto rr = __builtin_amdgcn_permlane32_swap(__float_as_uint(pmax), __float_as_uint(pmax), false, false);
;     pmax = fmaxf(__uint_as_float(rr[0]), __uint_as_float(rr[1])); }
;   if (__builtin_expect(__all(pmax - m_reg <= THRP), 1)) { mn = m_reg; alpha = 1.f; }
;   else { mn = fmaxf(m_reg, pmax); alpha = __builtin_amdgcn_exp2f((m_reg - mn) * CC); m_reg = mn; }
; template <int D0> DI void pv_one(f32x16& od, int vb, bf16x8 pa0, bf16x8 pa1, bf16x8 pa2, bf16x8 pa3) {
;   const s16x4 l0 = tr_read<v_rd_off(D0, 0, 0)>(vb), h0 = tr_read<v_rd_off(D0, 0, 1)>(vb), l1 = tr_read<v_rd_off(D0, 1, 0)>(vb), h1 = tr_read<v_rd_off(D0, 1, 1)>(vb);
;   const s16x4 l2 = tr_read<v_rd_off(D0, 2, 0)>(vb), h2 = tr_read<v_rd_off(D0, 2, 1)>(vb), l3 = tr_read<v_rd_off(D0, 3, 0)>(vb), h3 = tr_read<v_rd_off(D0, 3, 1)>(vb);
;   asm volatile("s_waitcnt lgkmcnt(0)" ::: "memory"); SBAR();
;     ...
;   od = __builtin_amdgcn_mfma_f32_32x32x16_bf16(pa0, PK(l0, h0), od, 0, 0, 0);
;   od = __builtin_amdgcn_mfma_f32_32x32x16_bf16(pa1, PK(l1, h1), od, 0, 0, 0);
;   od = __builtin_amdgcn_mfma_f32_32x32x16_bf16(pa2, PK(l2, h2), od, 0, 0, 0);
;   od = __builtin_amdgcn_mfma_f32_32x32x16_bf16(pa3, PK(l3, h3), od, 0, 0, 0);
;     ...
; }
; DI void pv_d0(f32x16* o, int vb, bf16x8 pa0, bf16x8 pa1, bf16x8 pa2, bf16x8 pa3) {
;   pv_one<0>(o[0], vb, pa0, pa1, pa2, pa3); pv_one<1>(o[1], vb, pa0, pa1, pa2, pa3); pv_one<2>(o[2], vb, pa0, pa1, pa2, pa3); pv_one<3>(o[3], vb, pa0, pa1, pa2, pa3);
.Lqsme_join:
	s_add_i32 s98, s19, -2
	s_cmp_lt_i32 s98, s12
	s_cbranch_scc1 .Lpvme_skip
	s_cmp_gt_i32 s98, s21
	s_cbranch_scc1 .Lpvme_skip
	ds_read_b64_tr_b16 v[70:71], v216 offset:0
	ds_read_b64_tr_b16 v[72:73], v216 offset:0x800
	ds_read_b64_tr_b16 v[114:115], v216 offset:0x1000
	ds_read_b64_tr_b16 v[116:117], v216 offset:0x1800
	ds_read_b64_tr_b16 v[124:125], v216 offset:0x2000
	ds_read_b64_tr_b16 v[126:127], v216 offset:0x2800
	ds_read_b64_tr_b16 v[128:129], v216 offset:0x3000
	ds_read_b64_tr_b16 v[130:131], v216 offset:0x3800
	s_waitcnt lgkmcnt(0)
	s_nop 0
	v_mfma_f32_32x32x16_bf16 v[0:15], v[132:135], v[70:73], v[0:15]
	ds_read_b64_tr_b16 v[70:71], v216 offset:0x200
	ds_read_b64_tr_b16 v[72:73], v216 offset:0xa00
	v_mfma_f32_32x32x16_bf16 v[0:15], v[66:69], v[114:117], v[0:15]
	ds_read_b64_tr_b16 v[114:115], v216 offset:0x1200
	ds_read_b64_tr_b16 v[116:117], v216 offset:0x1a00
	v_mfma_f32_32x32x16_bf16 v[0:15], v[108:111], v[124:127], v[0:15]
	ds_read_b64_tr_b16 v[124:125], v216 offset:0x2200
	ds_read_b64_tr_b16 v[126:127], v216 offset:0x2a00
	v_mfma_f32_32x32x16_bf16 v[0:15], v[120:123], v[128:131], v[0:15]
	ds_read_b64_tr_b16 v[128:129], v216 offset:0x3200
	ds_read_b64_tr_b16 v[130:131], v216 offset:0x3a00
	s_waitcnt lgkmcnt(0)
	v_mfma_f32_32x32x16_bf16 v[48:63], v[132:135], v[70:73], v[48:63]
	ds_read_b64_tr_b16 v[70:71], v216 offset:0x400
	ds_read_b64_tr_b16 v[72:73], v216 offset:0xc00
	v_mfma_f32_32x32x16_bf16 v[48:63], v[66:69], v[114:117], v[48:63]
	ds_read_b64_tr_b16 v[114:115], v216 offset:0x1400
	ds_read_b64_tr_b16 v[116:117], v216 offset:0x1c00
	v_mfma_f32_32x32x16_bf16 v[48:63], v[108:111], v[124:127], v[48:63]
	ds_read_b64_tr_b16 v[124:125], v216 offset:0x2400
	ds_read_b64_tr_b16 v[126:127], v216 offset:0x2c00
	v_mfma_f32_32x32x16_bf16 v[48:63], v[120:123], v[128:131], v[48:63]
	ds_read_b64_tr_b16 v[128:129], v216 offset:0x3400
	ds_read_b64_tr_b16 v[130:131], v216 offset:0x3c00
	s_waitcnt lgkmcnt(0)
	v_mfma_f32_32x32x16_bf16 v[32:47], v[132:135], v[70:73], v[32:47]
	ds_read_b64_tr_b16 v[70:71], v216 offset:0x600
	ds_read_b64_tr_b16 v[72:73], v216 offset:0xe00
	v_mfma_f32_32x32x16_bf16 v[32:47], v[66:69], v[114:117], v[32:47]
	ds_read_b64_tr_b16 v[114:115], v216 offset:0x1600
	ds_read_b64_tr_b16 v[116:117], v216 offset:0x1e00
	v_mfma_f32_32x32x16_bf16 v[32:47], v[108:111], v[124:127], v[32:47]
	ds_read_b64_tr_b16 v[124:125], v216 offset:0x2600
	ds_read_b64_tr_b16 v[126:127], v216 offset:0x2e00
	v_mfma_f32_32x32x16_bf16 v[32:47], v[120:123], v[128:131], v[32:47]
	ds_read_b64_tr_b16 v[128:129], v216 offset:0x3600
	ds_read_b64_tr_b16 v[130:131], v216 offset:0x3e00
	s_waitcnt lgkmcnt(0)
	v_mfma_f32_32x32x16_bf16 v[16:31], v[132:135], v[70:73], v[16:31]
	s_add_i32 s14, s19, -1
	s_cmp_le_i32 s19, s12
	s_cselect_b64 s[12:13], -1, 0
	s_cmp_gt_i32 s14, s21
	s_cselect_b64 s[14:15], -1, 0
	s_or_b64 vcc, s[12:13], s[14:15]
	v_cndmask_b32_e32 v74, v74, v211, vcc
	v_cndmask_b32_e32 v75, v75, v211, vcc
	v_mfma_f32_32x32x16_bf16 v[16:31], v[66:69], v[114:117], v[16:31]
	v_cndmask_b32_e32 v69, v94, v211, vcc
	v_cndmask_b32_e32 v94, v95, v211, vcc
	v_max_f32_e32 v64, v75, v75
	v_max_f32_e32 v95, v74, v74
	v_cndmask_b32_e32 v76, v76, v211, vcc
	v_cndmask_b32_e32 v77, v77, v211, vcc
	v_max_f32_e32 v64, v95, v64
	v_cndmask_b32_e32 v78, v78, v211, vcc
	v_cndmask_b32_e32 v79, v79, v211, vcc
	v_max3_f32 v64, v64, v76, v77
	v_cndmask_b32_e32 v80, v80, v211, vcc
	v_cndmask_b32_e32 v81, v81, v211, vcc
	v_max3_f32 v64, v64, v78, v79
	v_cndmask_b32_e32 v82, v82, v211, vcc
	v_cndmask_b32_e32 v83, v83, v211, vcc
	v_max3_f32 v64, v64, v80, v81
	v_cndmask_b32_e32 v84, v84, v211, vcc
	v_cndmask_b32_e32 v85, v85, v211, vcc
	v_max3_f32 v64, v64, v82, v83
	v_cndmask_b32_e32 v86, v86, v211, vcc
	v_cndmask_b32_e32 v87, v87, v211, vcc
	v_max3_f32 v64, v64, v84, v85
	v_cndmask_b32_e32 v88, v88, v211, vcc
	v_cndmask_b32_e32 v89, v89, v211, vcc
	v_max3_f32 v64, v64, v86, v87
	v_mfma_f32_32x32x16_bf16 v[16:31], v[108:111], v[124:127], v[16:31]
	v_cndmask_b32_e32 v90, v90, v211, vcc
	v_cndmask_b32_e32 v91, v91, v211, vcc
	v_max3_f32 v64, v64, v88, v89
	v_cndmask_b32_e32 v92, v92, v211, vcc
	v_cndmask_b32_e32 v93, v93, v211, vcc
	v_max3_f32 v64, v64, v90, v91
	v_max3_f32 v64, v64, v92, v93
	v_cndmask_b32_e32 v67, v96, v211, vcc
	v_cndmask_b32_e32 v68, v97, v211, vcc
	v_max3_f32 v64, v64, v69, v94
	v_cndmask_b32_e32 v98, v98, v211, vcc
	v_cndmask_b32_e32 v66, v99, v211, vcc
	v_max3_f32 v64, v64, v67, v68
	v_cndmask_b32_e32 v73, v100, v211, vcc
	v_cndmask_b32_e32 v100, v101, v211, vcc
	v_max3_f32 v64, v64, v98, v66
	v_cndmask_b32_e32 v72, v102, v211, vcc
	v_cndmask_b32_e32 v71, v103, v211, vcc
	v_max3_f32 v64, v64, v73, v100
	v_cndmask_b32_e32 v65, v104, v211, vcc
	v_cndmask_b32_e32 v70, v105, v211, vcc
	v_max3_f32 v64, v64, v72, v71
	v_mfma_f32_32x32x16_bf16 v[16:31], v[120:123], v[128:131], v[16:31]
	v_max3_f32 v64, v64, v65, v70
	v_mov_b32_e32 v95, v64
	s_nop 1
	v_permlane32_swap_b32_e32 v64, v95
	v_max_f32_e32 v95, v95, v95
	v_max_f32_e32 v64, v64, v64
	v_max_f32_e32 v95, v64, v95
	v_sub_f32_e32 v64, v95, v203
	v_cmp_ge_f32_e32 vcc, s84, v64
	s_cmp_eq_u64 vcc, exec
	v_mov_b32_e32 v64, 1.0
.Lpvme_join:
	s_cbranch_scc0 .LBB0_368
; DI void finishSM(f32x16& p0, f32x16& p1, float alpha, float& l_reg, bf16x8& pa0, bf16x8& pa1, bf16x8& pa2, bf16x8& pa3) {
; #pragma unroll
;   for (int r = 0; r < 16; ++r) p1[r] = __builtin_amdgcn_exp2f(p1[r]);
;   float ps = 0;
; #pragma unroll
;   for (int r = 0; r < 16; ++r) ps += p0[r];
; #pragma unroll
;   for (int r = 0; r < 16; ++r) ps += p1[r];
;   { auto rr = __builtin_amdgcn_permlane32_swap(__float_as_uint(ps), __float_as_uint(ps), false, false);
;     ps = __uint_as_float(rr[0]) + __uint_as_float(rr[1]); }
;   l_reg = l_reg * alpha + ps;
;     ...
;   PK4(p0, 0, pa0); PK4(p0, 8, pa1); PK4(p1, 0, pa2); PK4(p1, 8, pa3);
.LBB0_359:
	v_cmp_gt_f32_e32 vcc, 1.0, v64
	s_barrier
	s_cbranch_vccz .LBB0_363
	s_and_saveexec_b64 s[12:13], s[42:43]
	ds_write_b32 v200, v64 offset:128
	s_or_b64 exec, exec, s[12:13]
	s_waitcnt lgkmcnt(0)
	v_add_u32_e32 v95, s18, v190
	ds_read_b128 v[102:105], v95 offset:224
	ds_read_b128 v[108:111], v95 offset:192
	ds_read_b128 v[114:117], v95 offset:160
	ds_read_b128 v[118:121], v95 offset:128
	s_waitcnt lgkmcnt(3)
	v_pk_mul_f32 v[12:13], v[12:13], v[102:103]
	s_waitcnt lgkmcnt(2)
	v_pk_mul_f32 v[8:9], v[8:9], v[108:109]
	s_waitcnt lgkmcnt(1)
	v_pk_mul_f32 v[4:5], v[4:5], v[114:115]
	v_pk_mul_f32 v[14:15], v[14:15], v[104:105]
	v_pk_mul_f32 v[10:11], v[10:11], v[110:111]
	v_pk_mul_f32 v[6:7], v[6:7], v[116:117]
	s_waitcnt lgkmcnt(0)
	v_pk_mul_f32 v[2:3], v[2:3], v[120:121]
	v_pk_mul_f32 v[0:1], v[0:1], v[118:119]
	v_pk_mul_f32 v[60:61], v[60:61], v[102:103]
	v_pk_mul_f32 v[56:57], v[56:57], v[108:109]
	v_pk_mul_f32 v[52:53], v[52:53], v[114:115]
	v_pk_mul_f32 v[62:63], v[62:63], v[104:105]
	v_pk_mul_f32 v[58:59], v[58:59], v[110:111]
	v_pk_mul_f32 v[54:55], v[54:55], v[116:117]
	v_pk_mul_f32 v[50:51], v[50:51], v[120:121]
	v_pk_mul_f32 v[48:49], v[48:49], v[118:119]
	v_pk_mul_f32 v[44:45], v[44:45], v[102:103]
	v_pk_mul_f32 v[40:41], v[40:41], v[108:109]
	v_pk_mul_f32 v[36:37], v[36:37], v[114:115]
	v_pk_mul_f32 v[46:47], v[46:47], v[104:105]
	v_pk_mul_f32 v[42:43], v[42:43], v[110:111]
	v_pk_mul_f32 v[38:39], v[38:39], v[116:117]
	v_pk_mul_f32 v[34:35], v[34:35], v[120:121]
	v_pk_mul_f32 v[32:33], v[32:33], v[118:119]
	v_pk_mul_f32 v[28:29], v[28:29], v[102:103]
	v_pk_mul_f32 v[24:25], v[24:25], v[108:109]
	v_pk_mul_f32 v[20:21], v[20:21], v[114:115]
	v_pk_mul_f32 v[30:31], v[30:31], v[104:105]
	v_pk_mul_f32 v[26:27], v[26:27], v[110:111]
	v_pk_mul_f32 v[22:23], v[22:23], v[116:117]
	v_pk_mul_f32 v[18:19], v[18:19], v[120:121]
	v_pk_mul_f32 v[16:17], v[16:17], v[118:119]
.LBB0_363:
	v_mul_f32_e32 v95, 0xbdd53b94, v203
	v_fmamk_f32 v74, v74, 0x3dd53b94, v95
	v_fmamk_f32 v75, v75, 0x3dd53b94, v95
	v_fmamk_f32 v102, v82, 0x3dd53b94, v95
	v_exp_f32_e32 v82, v74
	v_fmamk_f32 v76, v76, 0x3dd53b94, v95
	v_fmamk_f32 v104, v84, 0x3dd53b94, v95
	v_exp_f32_e32 v84, v75
	v_fmamk_f32 v77, v77, 0x3dd53b94, v95
	v_fmamk_f32 v99, v80, 0x3dd53b94, v95
	v_exp_f32_e32 v80, v76
	v_fmamk_f32 v78, v78, 0x3dd53b94, v95
	v_fmamk_f32 v79, v79, 0x3dd53b94, v95
	v_fmamk_f32 v101, v81, 0x3dd53b94, v95
	v_fmamk_f32 v103, v83, 0x3dd53b94, v95
	v_exp_f32_e32 v83, v77
	v_fmamk_f32 v65, v65, 0x3dd53b94, v95
	v_exp_f32_e32 v78, v78
	v_exp_f32_e32 v81, v79
	v_exp_f32_e32 v79, v101
	v_exp_f32_e32 v101, v65
	v_add_f32_e32 v65, 0, v82
	v_add_f32_e32 v65, v84, v65
	v_exp_f32_e32 v77, v99
	v_add_f32_e32 v65, v80, v65
	v_add_f32_e32 v65, v83, v65
	v_exp_f32_e32 v74, v102
	v_add_f32_e32 v65, v78, v65
	v_exp_f32_e32 v76, v103
	v_add_f32_e32 v65, v81, v65
	v_fmamk_f32 v105, v85, 0x3dd53b94, v95
	v_fmamk_f32 v97, v72, 0x3dd53b94, v95
	v_exp_f32_e32 v72, v104
	v_add_f32_e32 v65, v77, v65
	v_fmamk_f32 v108, v86, 0x3dd53b94, v95
	v_exp_f32_e32 v75, v105
	v_add_f32_e32 v65, v79, v65
	v_fmamk_f32 v109, v87, 0x3dd53b94, v95
	v_fmamk_f32 v87, v92, 0x3dd53b94, v95
	v_fmamk_f32 v92, v68, 0x3dd53b94, v95
	v_exp_f32_e32 v68, v108
	v_add_f32_e32 v65, v74, v65
	v_fmamk_f32 v110, v88, 0x3dd53b94, v95
	v_fmamk_f32 v85, v90, 0x3dd53b94, v95
	v_fmamk_f32 v90, v94, 0x3dd53b94, v95
	v_fmamk_f32 v94, v73, 0x3dd53b94, v95
	v_exp_f32_e32 v73, v109
	v_add_f32_e32 v65, v76, v65
	v_fmamk_f32 v111, v89, 0x3dd53b94, v95
	v_fmamk_f32 v86, v91, 0x3dd53b94, v95
	v_fmamk_f32 v91, v67, 0x3dd53b94, v95
	v_exp_f32_e32 v67, v110
	v_add_f32_e32 v65, v72, v65
	v_fmamk_f32 v89, v69, 0x3dd53b94, v95
	v_exp_f32_e32 v69, v111
	v_add_f32_e32 v65, v75, v65
	v_fmamk_f32 v88, v93, 0x3dd53b94, v95
	v_fmamk_f32 v93, v98, 0x3dd53b94, v95
	v_exp_f32_e32 v98, v85
	v_add_f32_e32 v65, v68, v65
	v_exp_f32_e32 v86, v86
	v_add_f32_e32 v65, v73, v65
	v_exp_f32_e32 v87, v87
	v_add_f32_e32 v65, v67, v65
	v_exp_f32_e32 v88, v88
	v_add_f32_e32 v65, v69, v65
	v_exp_f32_e32 v89, v89
	v_add_f32_e32 v65, v98, v65
	v_exp_f32_e32 v90, v90
	v_add_f32_e32 v65, v86, v65
	v_exp_f32_e32 v91, v91
	v_add_f32_e32 v65, v87, v65
	v_exp_f32_e32 v92, v92
	v_add_f32_e32 v65, v88, v65
	v_fmamk_f32 v66, v66, 0x3dd53b94, v95
	v_exp_f32_e32 v93, v93
	v_add_f32_e32 v65, v89, v65
	v_exp_f32_e32 v99, v66
	v_add_f32_e32 v65, v90, v65
	v_fmamk_f32 v96, v100, 0x3dd53b94, v95
	v_exp_f32_e32 v94, v94
	v_add_f32_e32 v65, v91, v65
	v_exp_f32_e32 v96, v96
	v_add_f32_e32 v65, v92, v65
	v_fmamk_f32 v71, v71, 0x3dd53b94, v95
	v_exp_f32_e32 v97, v97
	v_add_f32_e32 v65, v93, v65
	v_exp_f32_e32 v100, v71
	v_add_f32_e32 v65, v99, v65
	v_fmac_f32_e32 v95, 0x3dd53b94, v70
	v_add_f32_e32 v65, v94, v65
	v_exp_f32_e32 v95, v95
	v_add_f32_e32 v65, v96, v65
	v_add_f32_e32 v65, v97, v65
	v_add_f32_e32 v65, v100, v65
	v_add_f32_e32 v65, v101, v65
	v_add_f32_e32 v65, v95, v65
	v_mov_b32_e32 v66, v65
	s_nop 1
	v_permlane32_swap_b32_e32 v65, v66
	v_cvt_pk_bf16_f32 v82, v82, v84
	v_cvt_pk_bf16_f32 v83, v80, v83
	v_cvt_pk_bf16_f32 v84, v78, v81
	v_cvt_pk_bf16_f32 v85, v77, v79
	v_cvt_pk_bf16_f32 v70, v74, v76
	v_cvt_pk_bf16_f32 v71, v72, v75
	v_cvt_pk_bf16_f32 v72, v68, v73
	v_cvt_pk_bf16_f32 v73, v67, v69
	v_cvt_pk_bf16_f32 v74, v98, v86
	v_cvt_pk_bf16_f32 v75, v87, v88
	v_cvt_pk_bf16_f32 v76, v89, v90
	v_cvt_pk_bf16_f32 v77, v91, v92
	v_cvt_pk_bf16_f32 v78, v93, v99
	v_cvt_pk_bf16_f32 v79, v94, v96
	v_cvt_pk_bf16_f32 v80, v97, v100
	v_cvt_pk_bf16_f32 v81, v101, v95
	s_nop 0
	v_permlane32_swap_b32_e32 v82, v84
	v_permlane32_swap_b32_e32 v83, v85
	v_permlane32_swap_b32_e32 v70, v72
	v_permlane32_swap_b32_e32 v71, v73
	v_permlane32_swap_b32_e32 v74, v76
	v_permlane32_swap_b32_e32 v75, v77
	v_permlane32_swap_b32_e32 v78, v80
	v_permlane32_swap_b32_e32 v79, v81
	s_max_i32 s98, s34, 0
	s_cmp_le_i32 s19, s98
	s_cbranch_scc1 .Lpvmf_skip
; #define LAS __attribute__((address_space(3)))
; DI unsigned cvtpk(float lo, float hi) { unsigned r; asm volatile("v_cvt_pk_bf16_f32 %0, %1, %2" : "=v"(r) : "v"(lo), "v"(hi)); return r; }
; #define SBAR() __builtin_amdgcn_sched_barrier(0)
; DI int crow(int r, int hi) { return (r & 3) + 8 * (r >> 2) + 4 * hi; }
; template <int OFF> DI s16x4 tr_read(int vb) { s16x4 r; asm volatile("ds_read_b64_tr_b16 %0, %1 offset:%2" : "=&v"(r) : "v"(vb), "i"(OFF) : "memory"); return r; }
; template <int D0> DI void pv_one(f32x16& od, int vb, bf16x8 pa0, bf16x8 pa1, bf16x8 pa2, bf16x8 pa3) {
;   const s16x4 l0 = tr_read<v_rd_off(D0, 0, 0)>(vb), h0 = tr_read<v_rd_off(D0, 0, 1)>(vb), l1 = tr_read<v_rd_off(D0, 1, 0)>(vb), h1 = tr_read<v_rd_off(D0, 1, 1)>(vb);
;   const s16x4 l2 = tr_read<v_rd_off(D0, 2, 0)>(vb), h2 = tr_read<v_rd_off(D0, 2, 1)>(vb), l3 = tr_read<v_rd_off(D0, 3, 0)>(vb), h3 = tr_read<v_rd_off(D0, 3, 1)>(vb);
;   asm volatile("s_waitcnt lgkmcnt(0)" ::: "memory"); SBAR();
;     ...
;   od = __builtin_amdgcn_mfma_f32_32x32x16_bf16(pa0, PK(l0, h0), od, 0, 0, 0);
;   od = __builtin_amdgcn_mfma_f32_32x32x16_bf16(pa1, PK(l1, h1), od, 0, 0, 0);
;   od = __builtin_amdgcn_mfma_f32_32x32x16_bf16(pa2, PK(l2, h2), od, 0, 0, 0);
;   od = __builtin_amdgcn_mfma_f32_32x32x16_bf16(pa3, PK(l3, h3), od, 0, 0, 0);
;     ...
; }
; DI void pv_d0(f32x16* o, int vb, bf16x8 pa0, bf16x8 pa1, bf16x8 pa2, bf16x8 pa3) {
;   pv_one<0>(o[0], vb, pa0, pa1, pa2, pa3); pv_one<1>(o[1], vb, pa0, pa1, pa2, pa3); pv_one<2>(o[2], vb, pa0, pa1, pa2, pa3); pv_one<3>(o[3], vb, pa0, pa1, pa2, pa3);
; template <bool BAND, int SD, bool ACT> DI void attn_unit_(const Unit& U, LAS char* lds, float C) {
;     ...
;     if (hi == 0) li_l[r32] = l_reg; asm volatile("s_waitcnt lgkmcnt(0)" ::: "memory");
;     float rli[16];
; #pragma unroll
;     for (int r = 0; r < 16; ++r) rli[r] = __builtin_amdgcn_rcpf(li_l[crow(r, hi)]);
;     LAS char* stg = lds + (wid < 2 ? OFF_V + wid * 8192 : OFF_K + (wid - 2) * 8192);
; #pragma unroll
;     for (int r = 0; r < 16; ++r) { const int orow = crow(r, hi);
; #pragma unroll
;       for (int d0 = 0; d0 < 4; ++d0) *(LAS bf16*)(stg + orow * 256 + (d0 * 32 + r32) * 2) = (bf16)(cvtpk(o[d0][r] * rli[r], 0.f) & 0xffffu); }
	s_add_i32 s98, s19, -1
	s_cmp_gt_i32 s98, s21
	s_cbranch_scc1 .Lpvmf_skip
	ds_read_b64_tr_b16 v[86:87], v202 offset:0
	ds_read_b64_tr_b16 v[88:89], v202 offset:0x800
	ds_read_b64_tr_b16 v[90:91], v202 offset:0x1000
	ds_read_b64_tr_b16 v[92:93], v202 offset:0x1800
	ds_read_b64_tr_b16 v[94:95], v202 offset:0x2000
	ds_read_b64_tr_b16 v[96:97], v202 offset:0x2800
	ds_read_b64_tr_b16 v[98:99], v202 offset:0x3000
	ds_read_b64_tr_b16 v[100:101], v202 offset:0x3800
	s_waitcnt lgkmcnt(0)
	s_nop 0
	v_mfma_f32_32x32x16_bf16 v[0:15], v[82:85], v[86:89], v[0:15]
	ds_read_b64_tr_b16 v[86:87], v202 offset:0x200
	ds_read_b64_tr_b16 v[88:89], v202 offset:0xa00
	v_mfma_f32_32x32x16_bf16 v[0:15], v[70:73], v[90:93], v[0:15]
	ds_read_b64_tr_b16 v[90:91], v202 offset:0x1200
	ds_read_b64_tr_b16 v[92:93], v202 offset:0x1a00
	v_mfma_f32_32x32x16_bf16 v[0:15], v[74:77], v[94:97], v[0:15]
	ds_read_b64_tr_b16 v[94:95], v202 offset:0x2200
	ds_read_b64_tr_b16 v[96:97], v202 offset:0x2a00
	v_mfma_f32_32x32x16_bf16 v[0:15], v[78:81], v[98:101], v[0:15]
	ds_read_b64_tr_b16 v[98:99], v202 offset:0x3200
	ds_read_b64_tr_b16 v[100:101], v202 offset:0x3a00
	s_waitcnt lgkmcnt(0)
	v_mfma_f32_32x32x16_bf16 v[48:63], v[82:85], v[86:89], v[48:63]
	ds_read_b64_tr_b16 v[86:87], v202 offset:0x400
	ds_read_b64_tr_b16 v[88:89], v202 offset:0xc00
	v_mfma_f32_32x32x16_bf16 v[48:63], v[70:73], v[90:93], v[48:63]
	ds_read_b64_tr_b16 v[90:91], v202 offset:0x1400
	ds_read_b64_tr_b16 v[92:93], v202 offset:0x1c00
	v_mfma_f32_32x32x16_bf16 v[48:63], v[74:77], v[94:97], v[48:63]
	ds_read_b64_tr_b16 v[94:95], v202 offset:0x2400
	ds_read_b64_tr_b16 v[96:97], v202 offset:0x2c00
	v_mfma_f32_32x32x16_bf16 v[48:63], v[78:81], v[98:101], v[48:63]
	ds_read_b64_tr_b16 v[98:99], v202 offset:0x3400
	ds_read_b64_tr_b16 v[100:101], v202 offset:0x3c00
	s_waitcnt lgkmcnt(0)
	v_mfma_f32_32x32x16_bf16 v[32:47], v[82:85], v[86:89], v[32:47]
	ds_read_b64_tr_b16 v[86:87], v202 offset:0x600
	ds_read_b64_tr_b16 v[88:89], v202 offset:0xe00
	v_mfma_f32_32x32x16_bf16 v[32:47], v[70:73], v[90:93], v[32:47]
	ds_read_b64_tr_b16 v[90:91], v202 offset:0x1600
	ds_read_b64_tr_b16 v[92:93], v202 offset:0x1e00
	v_mfma_f32_32x32x16_bf16 v[32:47], v[74:77], v[94:97], v[32:47]
	ds_read_b64_tr_b16 v[94:95], v202 offset:0x2600
	ds_read_b64_tr_b16 v[96:97], v202 offset:0x2e00
	v_mfma_f32_32x32x16_bf16 v[32:47], v[78:81], v[98:101], v[32:47]
	ds_read_b64_tr_b16 v[98:99], v202 offset:0x3600
	ds_read_b64_tr_b16 v[100:101], v202 offset:0x3e00
	s_waitcnt lgkmcnt(0)
	v_mfma_f32_32x32x16_bf16 v[16:31], v[82:85], v[86:89], v[16:31]
	v_mfma_f32_32x32x16_bf16 v[16:31], v[70:73], v[90:93], v[16:31]
	v_mfma_f32_32x32x16_bf16 v[16:31], v[74:77], v[94:97], v[16:31]
	v_mfma_f32_32x32x16_bf16 v[16:31], v[78:81], v[98:101], v[16:31]
.Lpvmf_join:
	s_and_saveexec_b64 s[12:13], s[42:43]
	v_add_f32_e32 v67, v106, v107
	v_fmac_f32_e32 v67, v201, v177
	v_add_f32_e32 v65, v65, v66
	v_fmac_f32_e32 v65, v67, v64
	ds_write_b32 v200, v65
	s_or_b64 exec, exec, s[12:13]
	s_waitcnt lgkmcnt(0)
	v_add_u32_e32 v72, s18, v190
	ds_read_b128 v[64:67], v72
	ds_read_b128 v[68:71], v72 offset:32
	s_lshl_b32 s12, s20, 13
	s_add_i32 s13, s12, 0x4000
	s_cmp_lt_i32 s20, 2
	s_waitcnt lgkmcnt(1)
	v_rcp_f32_e32 v73, v64
	s_cselect_b32 s12, s12, s13
	v_rcp_f32_e32 v74, v65
	v_rcp_f32_e32 v75, v66
	v_rcp_f32_e32 v76, v67
	s_waitcnt lgkmcnt(0)
	v_rcp_f32_e32 v77, v68
	ds_read_b128 v[64:67], v72 offset:64
	v_rcp_f32_e32 v78, v69
	v_rcp_f32_e32 v79, v70
	v_rcp_f32_e32 v80, v71
	ds_read_b128 v[68:71], v72 offset:96
	s_add_i32 s12, s12, 0
	v_lshlrev_b32_e32 v72, 10, v199
	v_lshlrev_b32_e32 v81, 1, v198
	v_mul_f32_e32 v0, v0, v73
	v_add3_u32 v72, s12, v72, v81
	v_cvt_pk_bf16_f32 v0, v0, v113
	ds_write_b16 v72, v0
	v_mul_f32_e32 v0, v48, v73
	v_cvt_pk_bf16_f32 v0, v0, v113
	ds_write_b16 v72, v0 offset:64
	v_mul_f32_e32 v0, v32, v73
	v_cvt_pk_bf16_f32 v0, v0, v113
	ds_write_b16 v72, v0 offset:128
	v_mul_f32_e32 v0, v16, v73
	v_cvt_pk_bf16_f32 v0, v0, v113
	ds_write_b16 v72, v0 offset:192
	v_mul_f32_e32 v0, v1, v74
	v_cvt_pk_bf16_f32 v0, v0, v113
	ds_write_b16 v72, v0 offset:256
	v_mul_f32_e32 v0, v49, v74
	v_cvt_pk_bf16_f32 v0, v0, v113
	ds_write_b16 v72, v0 offset:320
	v_mul_f32_e32 v0, v33, v74
	v_cvt_pk_bf16_f32 v0, v0, v113
	ds_write_b16 v72, v0 offset:384
	v_mul_f32_e32 v0, v17, v74
	v_cvt_pk_bf16_f32 v0, v0, v113
	ds_write_b16 v72, v0 offset:448
	v_mul_f32_e32 v0, v2, v75
	v_cvt_pk_bf16_f32 v0, v0, v113
	ds_write_b16 v72, v0 offset:512
	v_mul_f32_e32 v0, v50, v75
	v_cvt_pk_bf16_f32 v0, v0, v113
	ds_write_b16 v72, v0 offset:576
	v_mul_f32_e32 v0, v34, v75
	v_cvt_pk_bf16_f32 v0, v0, v113
	ds_write_b16 v72, v0 offset:640
	v_mul_f32_e32 v0, v18, v75
	v_cvt_pk_bf16_f32 v0, v0, v113
	ds_write_b16 v72, v0 offset:704
	v_mul_f32_e32 v0, v3, v76
	v_cvt_pk_bf16_f32 v0, v0, v113
	ds_write_b16 v72, v0 offset:768
	v_mul_f32_e32 v0, v51, v76
	v_cvt_pk_bf16_f32 v0, v0, v113
	ds_write_b16 v72, v0 offset:832
	v_mul_f32_e32 v0, v35, v76
	v_cvt_pk_bf16_f32 v0, v0, v113
	ds_write_b16 v72, v0 offset:896
	v_mul_f32_e32 v0, v19, v76
	v_cvt_pk_bf16_f32 v0, v0, v113
	ds_write_b16 v72, v0 offset:960
	v_mul_f32_e32 v0, v4, v77
	v_cvt_pk_bf16_f32 v0, v0, v113
	ds_write_b16 v72, v0 offset:2048
	v_mul_f32_e32 v0, v52, v77
	v_cvt_pk_bf16_f32 v0, v0, v113
	ds_write_b16 v72, v0 offset:2112
	v_mul_f32_e32 v0, v36, v77
	v_cvt_pk_bf16_f32 v0, v0, v113
	ds_write_b16 v72, v0 offset:2176
	v_mul_f32_e32 v0, v20, v77
	v_cvt_pk_bf16_f32 v0, v0, v113
	ds_write_b16 v72, v0 offset:2240
	v_mul_f32_e32 v0, v5, v78
	v_cvt_pk_bf16_f32 v0, v0, v113
	ds_write_b16 v72, v0 offset:2304
	v_mul_f32_e32 v0, v53, v78
	v_cvt_pk_bf16_f32 v0, v0, v113
	ds_write_b16 v72, v0 offset:2368
	v_mul_f32_e32 v0, v37, v78
	v_cvt_pk_bf16_f32 v0, v0, v113
	ds_write_b16 v72, v0 offset:2432
	v_mul_f32_e32 v0, v21, v78
	v_cvt_pk_bf16_f32 v0, v0, v113
	ds_write_b16 v72, v0 offset:2496
	v_mul_f32_e32 v0, v6, v79
	v_cvt_pk_bf16_f32 v0, v0, v113
	ds_write_b16 v72, v0 offset:2560
	v_mul_f32_e32 v0, v54, v79
	v_cvt_pk_bf16_f32 v0, v0, v113
	ds_write_b16 v72, v0 offset:2624
	v_mul_f32_e32 v0, v38, v79
	v_cvt_pk_bf16_f32 v0, v0, v113
	ds_write_b16 v72, v0 offset:2688
	v_mul_f32_e32 v0, v22, v79
	v_cvt_pk_bf16_f32 v0, v0, v113
	ds_write_b16 v72, v0 offset:2752
	v_mul_f32_e32 v0, v7, v80
	v_cvt_pk_bf16_f32 v0, v0, v113
	ds_write_b16 v72, v0 offset:2816
	v_mul_f32_e32 v0, v55, v80
	v_cvt_pk_bf16_f32 v0, v0, v113
	s_waitcnt lgkmcnt(14)
; #define LAS __attribute__((address_space(3)))
; DI unsigned cvtpk(float lo, float hi) { unsigned r; asm volatile("v_cvt_pk_bf16_f32 %0, %1, %2" : "=v"(r) : "v"(lo), "v"(hi)); return r; }
; DI int crow(int r, int hi) { return (r & 3) + 8 * (r >> 2) + 4 * hi; }
; template <bool BAND, int SD, bool ACT> DI void attn_unit_(const Unit& U, LAS char* lds, float C) {
;     ...
;     for (int r = 0; r < 16; ++r) { const int orow = crow(r, hi);
; #pragma unroll
;       for (int d0 = 0; d0 < 4; ++d0) *(LAS bf16*)(stg + orow * 256 + (d0 * 32 + r32) * 2) = (bf16)(cvtpk(o[d0][r] * rli[r], 0.f) & 0xffffu); }
;     asm volatile("s_waitcnt lgkmcnt(0)" ::: "memory");
;     bf16* Ow = U.O + (size_t)(wid * 32) * U.ldo;
; #pragma unroll
;     for (int i = 0; i < 8; ++i) { const int row = i * 4 + (lane >> 4), ch = lane & 15; const u32x4 v = *(const LAS u32x4*)(stg + row * 256 + ch * 16); *(u32x4*)(Ow + (size_t)row * U.ldo + ch * 8) = v; }
;   }
;   if (ACT && wid >= 4) __builtin_amdgcn_s_setprio(0);
	v_rcp_f32_e32 v64, v64
	ds_write_b16 v72, v0 offset:2880
	v_mul_f32_e32 v0, v39, v80
	v_cvt_pk_bf16_f32 v0, v0, v113
	ds_write_b16 v72, v0 offset:2944
	v_mul_f32_e32 v0, v23, v80
	v_cvt_pk_bf16_f32 v0, v0, v113
	ds_write_b16 v72, v0 offset:3008
	v_mul_f32_e32 v0, v8, v64
	v_cvt_pk_bf16_f32 v0, v0, v113
	ds_write_b16 v72, v0 offset:4096
	v_mul_f32_e32 v0, v56, v64
	v_cvt_pk_bf16_f32 v0, v0, v113
	v_rcp_f32_e32 v65, v65
	ds_write_b16 v72, v0 offset:4160
	v_mul_f32_e32 v0, v40, v64
	v_cvt_pk_bf16_f32 v0, v0, v113
	ds_write_b16 v72, v0 offset:4224
	v_mul_f32_e32 v0, v24, v64
	v_cvt_pk_bf16_f32 v0, v0, v113
	ds_write_b16 v72, v0 offset:4288
	v_mul_f32_e32 v0, v9, v65
	v_cvt_pk_bf16_f32 v0, v0, v113
	ds_write_b16 v72, v0 offset:4352
	v_mul_f32_e32 v0, v57, v65
	v_cvt_pk_bf16_f32 v0, v0, v113
	v_rcp_f32_e32 v66, v66
	ds_write_b16 v72, v0 offset:4416
	v_mul_f32_e32 v0, v41, v65
	v_cvt_pk_bf16_f32 v0, v0, v113
	ds_write_b16 v72, v0 offset:4480
	v_mul_f32_e32 v0, v25, v65
	v_cvt_pk_bf16_f32 v0, v0, v113
	ds_write_b16 v72, v0 offset:4544
	v_mul_f32_e32 v0, v10, v66
	v_cvt_pk_bf16_f32 v0, v0, v113
	ds_write_b16 v72, v0 offset:4608
	v_mul_f32_e32 v0, v58, v66
	v_cvt_pk_bf16_f32 v0, v0, v113
	v_rcp_f32_e32 v67, v67
	ds_write_b16 v72, v0 offset:4672
	v_mul_f32_e32 v0, v42, v66
	v_cvt_pk_bf16_f32 v0, v0, v113
	ds_write_b16 v72, v0 offset:4736
	v_mul_f32_e32 v0, v26, v66
	v_cvt_pk_bf16_f32 v0, v0, v113
	ds_write_b16 v72, v0 offset:4800
	v_mul_f32_e32 v0, v11, v67
	v_cvt_pk_bf16_f32 v0, v0, v113
	ds_write_b16 v72, v0 offset:4864
	v_mul_f32_e32 v0, v59, v67
	v_cvt_pk_bf16_f32 v0, v0, v113
	v_rcp_f32_e32 v68, v68
	ds_write_b16 v72, v0 offset:4928
	v_mul_f32_e32 v0, v43, v67
	v_cvt_pk_bf16_f32 v0, v0, v113
	ds_write_b16 v72, v0 offset:4992
	v_mul_f32_e32 v0, v27, v67
	v_cvt_pk_bf16_f32 v0, v0, v113
	ds_write_b16 v72, v0 offset:5056
	v_mul_f32_e32 v0, v12, v68
	v_cvt_pk_bf16_f32 v0, v0, v113
	ds_write_b16 v72, v0 offset:6144
	v_mul_f32_e32 v0, v60, v68
	v_cvt_pk_bf16_f32 v0, v0, v113
	v_rcp_f32_e32 v69, v69
	ds_write_b16 v72, v0 offset:6208
	v_mul_f32_e32 v0, v44, v68
	v_cvt_pk_bf16_f32 v0, v0, v113
	ds_write_b16 v72, v0 offset:6272
	v_mul_f32_e32 v0, v28, v68
	v_cvt_pk_bf16_f32 v0, v0, v113
	ds_write_b16 v72, v0 offset:6336
	v_mul_f32_e32 v0, v13, v69
	v_cvt_pk_bf16_f32 v0, v0, v113
	ds_write_b16 v72, v0 offset:6400
	v_mul_f32_e32 v0, v61, v69
	v_cvt_pk_bf16_f32 v0, v0, v113
	v_rcp_f32_e32 v70, v70
	ds_write_b16 v72, v0 offset:6464
	v_mul_f32_e32 v0, v45, v69
	v_cvt_pk_bf16_f32 v0, v0, v113
	ds_write_b16 v72, v0 offset:6528
	v_mul_f32_e32 v0, v29, v69
	v_cvt_pk_bf16_f32 v0, v0, v113
	ds_write_b16 v72, v0 offset:6592
	v_mul_f32_e32 v0, v14, v70
	v_cvt_pk_bf16_f32 v0, v0, v113
	ds_write_b16 v72, v0 offset:6656
	v_mul_f32_e32 v0, v62, v70
	v_cvt_pk_bf16_f32 v0, v0, v113
	v_rcp_f32_e32 v71, v71
	ds_write_b16 v72, v0 offset:6720
	v_mul_f32_e32 v0, v46, v70
	v_cvt_pk_bf16_f32 v0, v0, v113
	ds_write_b16 v72, v0 offset:6784
	v_mul_f32_e32 v0, v30, v70
	v_cvt_pk_bf16_f32 v0, v0, v113
	ds_write_b16 v72, v0 offset:6848
	v_mul_f32_e32 v0, v15, v71
	v_cvt_pk_bf16_f32 v0, v0, v113
	ds_write_b16 v72, v0 offset:6912
	v_mul_f32_e32 v0, v63, v71
	v_cvt_pk_bf16_f32 v0, v0, v113
	ds_write_b16 v72, v0 offset:6976
	v_mul_f32_e32 v0, v47, v71
	v_cvt_pk_bf16_f32 v0, v0, v113
	ds_write_b16 v72, v0 offset:7040
	v_mul_f32_e32 v0, v31, v71
	v_and_b32_e32 v112, 0xf0, v191
	v_cvt_pk_bf16_f32 v0, v0, v113
	ds_write_b16 v72, v0 offset:7104
	s_lshl_b32 s14, s20, 5
	v_lshrrev_b32_e32 v12, 4, v195
	v_add_u32_e32 v13, s12, v112
	s_waitcnt lgkmcnt(0)
	s_ashr_i32 s15, s14, 31
	v_lshl_add_u32 v0, v12, 8, v13
	v_or_b32_e32 v14, 4, v12
	s_lshl_b64 s[14:15], s[14:15], 12
	ds_read_b128 v[0:3], v0
	v_lshl_add_u32 v4, v14, 8, v13
	s_add_u32 s8, s8, s14
	ds_read_b128 v[4:7], v4
	s_addc_u32 s9, s9, s15
	v_lshl_add_u64 v[8:9], s[8:9], 0, v[112:113]
	v_lshlrev_b32_e32 v112, 12, v12
	v_lshl_add_u64 v[10:11], v[8:9], 0, v[112:113]
	v_lshlrev_b32_e32 v112, 12, v14
	s_waitcnt lgkmcnt(1)
	global_store_dwordx4 v[10:11], v[0:3], off
	v_or_b32_e32 v14, 12, v12
	s_andn2_b64 vcc, exec, s[10:11]
	v_lshl_add_u64 v[0:1], v[8:9], 0, v[112:113]
	s_waitcnt lgkmcnt(0)
	global_store_dwordx4 v[0:1], v[4:7], off
	s_nop 1
	v_or_b32_e32 v4, 8, v12
	v_lshl_add_u32 v0, v4, 8, v13
	ds_read_b128 v[0:3], v0
	v_lshlrev_b32_e32 v112, 12, v4
	v_lshl_add_u32 v4, v14, 8, v13
	ds_read_b128 v[4:7], v4
	v_lshl_add_u64 v[10:11], v[8:9], 0, v[112:113]
	v_lshlrev_b32_e32 v112, 12, v14
	s_waitcnt lgkmcnt(1)
	global_store_dwordx4 v[10:11], v[0:3], off
	v_or_b32_e32 v14, 20, v12
	s_nop 0
	v_lshl_add_u64 v[0:1], v[8:9], 0, v[112:113]
	s_waitcnt lgkmcnt(0)
	global_store_dwordx4 v[0:1], v[4:7], off
	s_nop 1
	v_or_b32_e32 v4, 16, v12
	v_lshl_add_u32 v0, v4, 8, v13
	ds_read_b128 v[0:3], v0
	v_lshlrev_b32_e32 v112, 12, v4
	v_lshl_add_u32 v4, v14, 8, v13
	ds_read_b128 v[4:7], v4
	v_lshl_add_u64 v[10:11], v[8:9], 0, v[112:113]
	v_lshlrev_b32_e32 v112, 12, v14
	s_waitcnt lgkmcnt(1)
	global_store_dwordx4 v[10:11], v[0:3], off
	s_nop 1
	v_lshl_add_u64 v[0:1], v[8:9], 0, v[112:113]
	s_waitcnt lgkmcnt(0)
	global_store_dwordx4 v[0:1], v[4:7], off
	s_nop 1
	v_or_b32_e32 v4, 24, v12
	v_lshl_add_u32 v0, v4, 8, v13
	v_or_b32_e32 v12, 28, v12
	ds_read_b128 v[0:3], v0
	v_lshlrev_b32_e32 v112, 12, v4
	v_lshl_add_u32 v4, v12, 8, v13
	ds_read_b128 v[4:7], v4
	v_lshl_add_u64 v[10:11], v[8:9], 0, v[112:113]
	v_lshlrev_b32_e32 v112, 12, v12
	s_waitcnt lgkmcnt(1)
	global_store_dwordx4 v[10:11], v[0:3], off
	s_nop 1
	v_lshl_add_u64 v[0:1], v[8:9], 0, v[112:113]
	s_waitcnt lgkmcnt(0)
	global_store_dwordx4 v[0:1], v[4:7], off
	s_cbranch_vccnz .LBB0_321
	s_setprio 0
	s_branch .LBB0_321
